# RWKV chunk: waves0-3 MFMA chain fragment reads triple-buffered; wave4 forward-substitution row reads prefetched via 12-quad ring
# baseline (speedup 1.0000x reference)
; __device__ __forceinline__ unsigned f2bf(float f) { return pk2(f, 0.f) & 0xffffu; }
; __device__ __forceinline__ unsigned opq(unsigned x) { asm volatile("" : "+v"(x)); return x; }
; __device__ __forceinline__ void rwkv_chunk_item(const Frame& F, ArgsRef A, int l, int item, bool last) {
;     ...
;         if (w == 4) {
;             const unsigned a_dgb = opq((unsigned)(RC_DG + g * 1024)), a_tbs = opq((unsigned)(RC_TB + (g * 256 + l16) * 2));
;             float tc[16]; const int lq = (int)opq((unsigned)l16);
; #pragma unroll
;             for (int t = 0; t < 16; ++t) {
;                 float acc = (t == lq) ? 1.f : 0.f;
;                 const f32x4 L0 = LD_(f32x4, a_dgb + t * 64), L1 = LD_(f32x4, a_dgb + t * 64 + 16), L2 = LD_(f32x4, a_dgb + t * 64 + 32), L3 = LD_(f32x4, a_dgb + t * 64 + 48);
;                 const float lr[16] = {L0[0], L0[1], L0[2], L0[3], L1[0], L1[1], L1[2], L1[3], L2[0], L2[1], L2[2], L2[3], L3[0], L3[1], L3[2], L3[3]};
; #pragma unroll
;                 for (int s = 0; s < 16; ++s) if (s < t) acc += lr[s] * tc[s];
;                 tc[t] = acc;
;                 ST_(unsigned short, a_tbs + t * 32) = (unsigned short)f2bf(acc);
;             }
;         }
.LBB0_795:
	s_andn2_b64 vcc, exec, s[76:77]
	s_waitcnt lgkmcnt(0)
	s_barrier
	s_cbranch_vccnz .LBB0_797
	v_lshl_add_u32 v0, v185, 10, v235
	v_mov_b32_e32 v3, v215
	v_mov_b32_e32 v1, v104
	s_nop 0
	v_cmp_eq_u32_e32 vcc, 0, v1
	v_add_u32_e32 v60, 0, v0
	v_add_u32_e32 v0, 0, v3
	ds_read_b128 v[66:69], v60 offset:64
	ds_read_b128 v[70:73], v60 offset:128
	ds_read_b128 v[74:77], v60 offset:192
	ds_read_b128 v[78:81], v60 offset:256
	ds_read_b128 v[92:95], v60 offset:320
	ds_read_b128 v[96:99], v60 offset:336
	ds_read_b128 v[100:103], v60 offset:384
	ds_read_b128 v[172:175], v60 offset:400
	ds_read_b128 v[176:179], v60 offset:448
	ds_read_b128 v[180:183], v60 offset:464
	ds_read_b128 v[196:199], v60 offset:512
	ds_read_b128 v[228:231], v60 offset:528
	v_cndmask_b32_e64 v3, 0, 1.0, vcc
	v_cvt_pk_bf16_f32 v91, v3, s0
	ds_write_b16 v0, v91
	v_cmp_eq_u32_e32 vcc, 1, v1
	s_nop 1
	v_cndmask_b32_e64 v61, 0, 1.0, vcc
	v_cmp_eq_u32_e32 vcc, 2, v1
	s_nop 1
	v_cndmask_b32_e64 v62, 0, 1.0, vcc
	v_cmp_eq_u32_e32 vcc, 3, v1
	s_nop 1
	v_cndmask_b32_e64 v63, 0, 1.0, vcc
	v_cmp_eq_u32_e32 vcc, 4, v1
	s_nop 1
	v_cndmask_b32_e64 v64, 0, 1.0, vcc
	v_cmp_eq_u32_e32 vcc, 5, v1
	s_nop 1
	v_cndmask_b32_e64 v65, 0, 1.0, vcc
	v_cmp_eq_u32_e32 vcc, 6, v1
	s_nop 1
	v_cndmask_b32_e64 v82, 0, 1.0, vcc
	v_cmp_eq_u32_e32 vcc, 7, v1
	s_nop 1
	v_cndmask_b32_e64 v83, 0, 1.0, vcc
	v_cmp_eq_u32_e32 vcc, 8, v1
	s_nop 1
	v_cndmask_b32_e64 v84, 0, 1.0, vcc
	v_cmp_eq_u32_e32 vcc, 9, v1
	s_nop 1
	v_cndmask_b32_e64 v85, 0, 1.0, vcc
	v_cmp_eq_u32_e32 vcc, 10, v1
	s_nop 1
	v_cndmask_b32_e64 v86, 0, 1.0, vcc
	v_cmp_eq_u32_e32 vcc, 11, v1
	s_nop 1
	v_cndmask_b32_e64 v87, 0, 1.0, vcc
	v_cmp_eq_u32_e32 vcc, 12, v1
	s_nop 1
	v_cndmask_b32_e64 v88, 0, 1.0, vcc
	v_cmp_eq_u32_e32 vcc, 13, v1
	s_nop 1
	v_cndmask_b32_e64 v89, 0, 1.0, vcc
	v_cmp_eq_u32_e32 vcc, 14, v1
	s_nop 1
	v_cndmask_b32_e64 v90, 0, 1.0, vcc
	v_cmp_eq_u32_e32 vcc, 15, v1
	s_nop 1
	v_cndmask_b32_e64 v1, 0, 1.0, vcc
	s_waitcnt lgkmcnt(12)
	v_fmac_f32_e32 v61, v3, v66
	v_cvt_pk_bf16_f32 v253, v61, s0
	ds_write_b16 v0, v253 offset:32
	ds_read_b128 v[66:69], v60 offset:576
	s_waitcnt lgkmcnt(13)
	v_fmac_f32_e32 v62, v3, v70
	v_fmac_f32_e32 v62, v61, v71
	v_cvt_pk_bf16_f32 v91, v62, s0
	ds_write_b16 v0, v91 offset:64
	ds_read_b128 v[70:73], v60 offset:592
	s_waitcnt lgkmcnt(14)
	v_fmac_f32_e32 v63, v3, v74
	v_fmac_f32_e32 v63, v61, v75
	v_fmac_f32_e32 v63, v62, v76
	v_cvt_pk_bf16_f32 v253, v63, s0
	ds_write_b16 v0, v253 offset:96
	s_waitcnt lgkmcnt(14)
	v_fmac_f32_e32 v64, v3, v78
	v_fmac_f32_e32 v64, v61, v79
	v_fmac_f32_e32 v64, v62, v80
	v_fmac_f32_e32 v64, v63, v81
	v_cvt_pk_bf16_f32 v91, v64, s0
	ds_write_b16 v0, v91 offset:128
	s_waitcnt lgkmcnt(13)
	v_fmac_f32_e32 v65, v3, v92
	v_fmac_f32_e32 v65, v61, v93
	v_fmac_f32_e32 v65, v62, v94
	v_fmac_f32_e32 v65, v63, v95
	v_fmac_f32_e32 v65, v64, v96
	v_cvt_pk_bf16_f32 v253, v65, s0
	ds_write_b16 v0, v253 offset:160
	ds_read_b128 v[74:77], v60 offset:608
	s_waitcnt lgkmcnt(13)
	v_fmac_f32_e32 v82, v3, v100
	v_fmac_f32_e32 v82, v61, v101
	v_fmac_f32_e32 v82, v62, v102
	v_fmac_f32_e32 v82, v63, v103
	v_fmac_f32_e32 v82, v64, v172
	v_fmac_f32_e32 v82, v65, v173
	v_cvt_pk_bf16_f32 v91, v82, s0
	ds_write_b16 v0, v91 offset:192
	ds_read_b128 v[78:81], v60 offset:640
	s_waitcnt lgkmcnt(13)
	v_fmac_f32_e32 v83, v3, v176
	v_fmac_f32_e32 v83, v61, v177
	v_fmac_f32_e32 v83, v62, v178
	v_fmac_f32_e32 v83, v63, v179
	v_fmac_f32_e32 v83, v64, v180
	v_fmac_f32_e32 v83, v65, v181
	v_fmac_f32_e32 v83, v82, v182
	v_cvt_pk_bf16_f32 v253, v83, s0
	ds_write_b16 v0, v253 offset:224
	ds_read_b128 v[92:95], v60 offset:656
	s_waitcnt lgkmcnt(13)
	v_fmac_f32_e32 v84, v3, v196
	v_fmac_f32_e32 v84, v61, v197
	v_fmac_f32_e32 v84, v62, v198
	v_fmac_f32_e32 v84, v63, v199
	v_fmac_f32_e32 v84, v64, v228
	v_fmac_f32_e32 v84, v65, v229
	v_fmac_f32_e32 v84, v82, v230
	v_fmac_f32_e32 v84, v83, v231
	v_cvt_pk_bf16_f32 v91, v84, s0
	ds_write_b16 v0, v91 offset:256
	ds_read_b128 v[96:99], v60 offset:672
	s_waitcnt lgkmcnt(6)
	v_fmac_f32_e32 v85, v3, v66
	v_fmac_f32_e32 v85, v61, v67
	v_fmac_f32_e32 v85, v62, v68
	v_fmac_f32_e32 v85, v63, v69
	v_fmac_f32_e32 v85, v64, v70
	v_fmac_f32_e32 v85, v65, v71
	v_fmac_f32_e32 v85, v82, v72
	v_fmac_f32_e32 v85, v83, v73
	v_fmac_f32_e32 v85, v84, v74
	v_cvt_pk_bf16_f32 v253, v85, s0
	ds_write_b16 v0, v253 offset:288
	ds_read_b128 v[100:103], v60 offset:704
	ds_read_b128 v[172:175], v60 offset:720
	ds_read_b128 v[176:179], v60 offset:736
	ds_read_b128 v[180:183], v60 offset:768
	ds_read_b128 v[196:199], v60 offset:784
	ds_read_b128 v[228:231], v60 offset:800
	ds_read_b128 v[66:69], v60 offset:832
	ds_read_b128 v[70:73], v60 offset:848
	s_waitcnt lgkmcnt(9)
	v_fmac_f32_e32 v86, v3, v78
	v_fmac_f32_e32 v86, v61, v79
	v_fmac_f32_e32 v86, v62, v80
	v_fmac_f32_e32 v86, v63, v81
	v_fmac_f32_e32 v86, v64, v92
	v_fmac_f32_e32 v86, v65, v93
	v_fmac_f32_e32 v86, v82, v94
	v_fmac_f32_e32 v86, v83, v95
	v_fmac_f32_e32 v86, v84, v96
	v_fmac_f32_e32 v86, v85, v97
	v_cvt_pk_bf16_f32 v91, v86, s0
	ds_write_b16 v0, v91 offset:320
	ds_read_b128 v[74:77], v60 offset:864
	ds_read_b128 v[78:81], v60 offset:880
	ds_read_b128 v[92:95], v60 offset:896
	ds_read_b128 v[96:99], v60 offset:912
	s_waitcnt lgkmcnt(10)
	v_fmac_f32_e32 v87, v3, v100
	v_fmac_f32_e32 v87, v61, v101
	v_fmac_f32_e32 v87, v62, v102
	v_fmac_f32_e32 v87, v63, v103
	v_fmac_f32_e32 v87, v64, v172
	v_fmac_f32_e32 v87, v65, v173
	v_fmac_f32_e32 v87, v82, v174
	v_fmac_f32_e32 v87, v83, v175
	v_fmac_f32_e32 v87, v84, v176
	v_fmac_f32_e32 v87, v85, v177
	v_fmac_f32_e32 v87, v86, v178
	v_cvt_pk_bf16_f32 v253, v87, s0
	ds_write_b16 v0, v253 offset:352
	ds_read_b128 v[100:103], v60 offset:928
	ds_read_b128 v[172:175], v60 offset:944
	ds_read_b128 v[176:179], v60 offset:960
	s_waitcnt lgkmcnt(11)
; __device__ __forceinline__ unsigned f2bf(float f) { return pk2(f, 0.f) & 0xffffu; }
; __device__ __forceinline__ void rwkv_chunk_item(const Frame& F, ArgsRef A, int l, int item, bool last) {
;     ...
;             for (int t = 0; t < 16; ++t) {
;                 float acc = (t == lq) ? 1.f : 0.f;
;                 const f32x4 L0 = LD_(f32x4, a_dgb + t * 64), L1 = LD_(f32x4, a_dgb + t * 64 + 16), L2 = LD_(f32x4, a_dgb + t * 64 + 32), L3 = LD_(f32x4, a_dgb + t * 64 + 48);
;                 const float lr[16] = {L0[0], L0[1], L0[2], L0[3], L1[0], L1[1], L1[2], L1[3], L2[0], L2[1], L2[2], L2[3], L3[0], L3[1], L3[2], L3[3]};
; #pragma unroll
;                 for (int s = 0; s < 16; ++s) if (s < t) acc += lr[s] * tc[s];
;                 tc[t] = acc;
;                 ST_(unsigned short, a_tbs + t * 32) = (unsigned short)f2bf(acc);
;             }
	v_fmac_f32_e32 v88, v3, v180
	v_fmac_f32_e32 v88, v61, v181
	v_fmac_f32_e32 v88, v62, v182
	v_fmac_f32_e32 v88, v63, v183
	v_fmac_f32_e32 v88, v64, v196
	v_fmac_f32_e32 v88, v65, v197
	v_fmac_f32_e32 v88, v82, v198
	v_fmac_f32_e32 v88, v83, v199
	v_fmac_f32_e32 v88, v84, v228
	v_fmac_f32_e32 v88, v85, v229
	v_fmac_f32_e32 v88, v86, v230
	v_fmac_f32_e32 v88, v87, v231
	v_cvt_pk_bf16_f32 v91, v88, s0
	ds_write_b16 v0, v91 offset:384
	ds_read_b128 v[180:183], v60 offset:976
	ds_read_b128 v[196:199], v60 offset:992
	ds_read_b128 v[228:231], v60 offset:1008
	s_waitcnt lgkmcnt(10)
	v_fmac_f32_e32 v89, v3, v66
	v_fmac_f32_e32 v89, v61, v67
	v_fmac_f32_e32 v89, v62, v68
	v_fmac_f32_e32 v89, v63, v69
	v_fmac_f32_e32 v89, v64, v70
	v_fmac_f32_e32 v89, v65, v71
	v_fmac_f32_e32 v89, v82, v72
	v_fmac_f32_e32 v89, v83, v73
	v_fmac_f32_e32 v89, v84, v74
	v_fmac_f32_e32 v89, v85, v75
	v_fmac_f32_e32 v89, v86, v76
	v_fmac_f32_e32 v89, v87, v77
	v_fmac_f32_e32 v89, v88, v78
	v_cvt_pk_bf16_f32 v253, v89, s0
	ds_write_b16 v0, v253 offset:416
	s_waitcnt lgkmcnt(6)
	v_fmac_f32_e32 v90, v3, v92
	v_fmac_f32_e32 v90, v61, v93
	v_fmac_f32_e32 v90, v62, v94
	v_fmac_f32_e32 v90, v63, v95
	v_fmac_f32_e32 v90, v64, v96
	v_fmac_f32_e32 v90, v65, v97
	v_fmac_f32_e32 v90, v82, v98
	v_fmac_f32_e32 v90, v83, v99
	v_fmac_f32_e32 v90, v84, v100
	v_fmac_f32_e32 v90, v85, v101
	v_fmac_f32_e32 v90, v86, v102
	v_fmac_f32_e32 v90, v87, v103
	v_fmac_f32_e32 v90, v88, v172
	v_fmac_f32_e32 v90, v89, v173
	v_cvt_pk_bf16_f32 v91, v90, s0
	ds_write_b16 v0, v91 offset:448
	s_waitcnt lgkmcnt(2)
	v_fmac_f32_e32 v1, v3, v176
	v_fmac_f32_e32 v1, v61, v177
	v_fmac_f32_e32 v1, v62, v178
	v_fmac_f32_e32 v1, v63, v179
	v_fmac_f32_e32 v1, v64, v180
	v_fmac_f32_e32 v1, v65, v181
	v_fmac_f32_e32 v1, v82, v182
	v_fmac_f32_e32 v1, v83, v183
	v_fmac_f32_e32 v1, v84, v196
	v_fmac_f32_e32 v1, v85, v197
	v_fmac_f32_e32 v1, v86, v198
	v_fmac_f32_e32 v1, v87, v199
	v_fmac_f32_e32 v1, v88, v228
	v_fmac_f32_e32 v1, v89, v229
	v_fmac_f32_e32 v1, v90, v230
	v_cvt_pk_bf16_f32 v253, v1, s0
	ds_write_b16 v0, v253 offset:480
; __device__ __forceinline__ void rwkv_chunk_item(const Frame& F, ArgsRef A, int l, int item, bool last) {
;     ...
;         if (w < 4) {
;             const bf16x8 sf0 = pack8(S[0], S[1]), sf1 = pack8(S[2], S[3]);
;             { const unsigned av = RC_VT + a_tr + (8 * g) * (RC_LD * 2) + w * 32; vb0 = tr8(L, av, av + 4 * RC_LD * 2); vb1 = tr8(L, av + 32 * RC_LD * 2, av + 36 * RC_LD * 2); }
; #pragma unroll
;             for (int mt = 0; mt < 4; ++mt) {
;                 const unsigned o4 = a_f4 + mt * (16 * RC_LD * 2), o8 = a_f8 + mt * (16 * RC_LD * 2);
;                 X[mt] = __builtin_amdgcn_mfma_f32_16x16x32_bf16(kperm(L, RC_QP + o4), sf0, zero4, 0, 0, 0);
;                 X[mt] = __builtin_amdgcn_mfma_f32_16x16x32_bf16(kperm(L, RC_QP + o4 + 64), sf1, X[mt], 0, 0, 0);
;                 X[mt] = __builtin_amdgcn_mfma_f32_16x16x32_bf16(LD_(bf16x8, RC_MKD + o8), vb0, X[mt], 0, 0, 0);
;                 X[mt] = __builtin_amdgcn_mfma_f32_16x16x32_bf16(LD_(bf16x8, RC_MKD + o8 + 64), vb1, X[mt], 0, 0, 0);
;                 O[mt] = __builtin_amdgcn_mfma_f32_16x16x32_bf16(kperm(L, RC_RT + o4), sf0, zero4, 0, 0, 0);
;                 O[mt] = __builtin_amdgcn_mfma_f32_16x16x32_bf16(kperm(L, RC_RT + o4 + 64), sf1, O[mt], 0, 0, 0);
;                 O[mt] = __builtin_amdgcn_mfma_f32_16x16x32_bf16(LD_(bf16x8, RC_NKD + o8), vb0, O[mt], 0, 0, 0);
;                 O[mt] = __builtin_amdgcn_mfma_f32_16x16x32_bf16(LD_(bf16x8, RC_NKD + o8 + 64), vb1, O[mt], 0, 0, 0);
;                 asm volatile("" ::: "memory");
;             }
; #pragma unroll
;             for (int jt = 0; jt < 4; ++jt) { const unsigned ak = RC_KD + a_tr + (8 * g) * (RC_LD * 2) + jt * 32;
;                 S[jt] = __builtin_amdgcn_mfma_f32_16x16x32_bf16(tr8(L, ak, ak + 4 * RC_LD * 2), vb0, S[jt], 0, 0, 0);
;                 S[jt] = __builtin_amdgcn_mfma_f32_16x16x32_bf16(tr8(L, ak + 32 * RC_LD * 2, ak + 36 * RC_LD * 2), vb1, S[jt], 0, 0, 0); }
.LBB0_797:
	v_cndmask_b32_e64 v0, 0, 1, s[78:79]
	v_cmp_ne_u32_e64 s[44:45], 1, v0
	s_andn2_b64 vcc, exec, s[78:79]
	s_cbranch_vccnz .LBB0_799
	ds_read_b64_tr_b16 v[64:65], v242 offset:55296
	ds_read_b64_tr_b16 v[66:67], v242 offset:55872
	ds_read_b64_tr_b16 v[60:61], v242 offset:59904
	ds_read_b64_tr_b16 v[62:63], v242 offset:60480
	v_add_u32_e32 v0, 0x12000, v111
	v_add_u32_e32 v1, 0x2000, v239
	ds_read2_b64 v[76:79], v239 offset1:4
	ds_read2_b64 v[80:83], v239 offset0:8 offset1:12
	ds_read_b128 v[84:87], v0
	ds_read_b128 v[88:91], v0 offset:64
	ds_read2_b64 v[92:95], v1 offset0:128 offset1:132
	ds_read2_b64 v[96:99], v1 offset0:136 offset1:140
	ds_read_b128 v[100:103], v0 offset:18432
	ds_read_b128 v[172:175], v0 offset:18496
	v_cvt_pk_bf16_f32 v68, v36, v37
	v_cvt_pk_bf16_f32 v69, v38, v39
	v_cvt_pk_bf16_f32 v70, v32, v33
	v_cvt_pk_bf16_f32 v71, v34, v35
	v_cvt_pk_bf16_f32 v72, v20, v21
	v_cvt_pk_bf16_f32 v73, v22, v23
	v_cvt_pk_bf16_f32 v74, v16, v17
	v_cvt_pk_bf16_f32 v75, v18, v19
	v_add_u32_e32 v3, 0x800, v239
	v_add_u32_e32 v170, 0x2800, v239
	v_add_u32_e32 v171, 0x1000, v239
	v_add_u32_e32 v192, 0x3000, v239
	v_add_u32_e32 v193, 0x1800, v239
	v_add_u32_e32 v200, 0x3800, v239
	v_add_u32_e32 v201, v106, v218
	s_waitcnt lgkmcnt(4)
	v_mfma_f32_16x16x32_bf16 v[12:15], v[76:79], v[68:71], 0
	v_mfma_f32_16x16x32_bf16 v[12:15], v[80:83], v[72:75], v[12:15]
	v_mfma_f32_16x16x32_bf16 v[12:15], v[84:87], v[64:67], v[12:15]
	v_mfma_f32_16x16x32_bf16 v[12:15], v[88:91], v[60:63], v[12:15]
	ds_read2_b64 v[176:179], v3 offset0:32 offset1:36
	ds_read2_b64 v[180:183], v3 offset0:40 offset1:44
	ds_read_b128 v[196:199], v0 offset:2304
	ds_read_b128 v[228:231], v0 offset:2368
	s_waitcnt lgkmcnt(4)
	v_mfma_f32_16x16x32_bf16 v[24:27], v[92:95], v[68:71], 0
	v_mfma_f32_16x16x32_bf16 v[24:27], v[96:99], v[72:75], v[24:27]
	v_mfma_f32_16x16x32_bf16 v[24:27], v[100:103], v[64:67], v[24:27]
	v_mfma_f32_16x16x32_bf16 v[24:27], v[172:175], v[60:63], v[24:27]
	ds_read2_b64 v[76:79], v170 offset0:160 offset1:164
	ds_read2_b64 v[80:83], v170 offset0:168 offset1:172
	ds_read_b128 v[84:87], v0 offset:20736
	ds_read_b128 v[88:91], v0 offset:20800
	s_waitcnt lgkmcnt(4)
	v_mfma_f32_16x16x32_bf16 v[28:31], v[176:179], v[68:71], 0
	v_mfma_f32_16x16x32_bf16 v[28:31], v[180:183], v[72:75], v[28:31]
	v_mfma_f32_16x16x32_bf16 v[28:31], v[196:199], v[64:67], v[28:31]
	v_mfma_f32_16x16x32_bf16 v[28:31], v[228:231], v[60:63], v[28:31]
	ds_read2_b64 v[92:95], v171 offset0:64 offset1:68
	ds_read2_b64 v[96:99], v171 offset0:72 offset1:76
	ds_read_b128 v[100:103], v0 offset:4608
	ds_read_b128 v[172:175], v0 offset:4672
	s_waitcnt lgkmcnt(4)
	v_mfma_f32_16x16x32_bf16 v[40:43], v[76:79], v[68:71], 0
	v_mfma_f32_16x16x32_bf16 v[40:43], v[80:83], v[72:75], v[40:43]
	v_mfma_f32_16x16x32_bf16 v[40:43], v[84:87], v[64:67], v[40:43]
	v_mfma_f32_16x16x32_bf16 v[40:43], v[88:91], v[60:63], v[40:43]
	ds_read2_b64 v[176:179], v192 offset0:192 offset1:196
	ds_read2_b64 v[180:183], v192 offset0:200 offset1:204
	ds_read_b128 v[196:199], v0 offset:23040
	ds_read_b128 v[228:231], v0 offset:23104
	s_waitcnt lgkmcnt(4)
	v_mfma_f32_16x16x32_bf16 v[44:47], v[92:95], v[68:71], 0
	v_mfma_f32_16x16x32_bf16 v[44:47], v[96:99], v[72:75], v[44:47]
	v_mfma_f32_16x16x32_bf16 v[44:47], v[100:103], v[64:67], v[44:47]
	v_mfma_f32_16x16x32_bf16 v[44:47], v[172:175], v[60:63], v[44:47]
	ds_read2_b64 v[76:79], v193 offset0:96 offset1:100
	ds_read2_b64 v[80:83], v193 offset0:104 offset1:108
	ds_read_b128 v[84:87], v0 offset:6912
	ds_read_b128 v[88:91], v0 offset:6976
	s_waitcnt lgkmcnt(4)
	v_mfma_f32_16x16x32_bf16 v[48:51], v[176:179], v[68:71], 0
	v_mfma_f32_16x16x32_bf16 v[48:51], v[180:183], v[72:75], v[48:51]
	v_mfma_f32_16x16x32_bf16 v[48:51], v[196:199], v[64:67], v[48:51]
	v_mfma_f32_16x16x32_bf16 v[48:51], v[228:231], v[60:63], v[48:51]
	ds_read2_b64 v[92:95], v200 offset0:224 offset1:228
	ds_read2_b64 v[96:99], v200 offset0:232 offset1:236
	ds_read_b128 v[100:103], v0 offset:25344
	ds_read_b128 v[172:175], v0 offset:25408
	s_waitcnt lgkmcnt(4)
	v_mfma_f32_16x16x32_bf16 v[52:55], v[76:79], v[68:71], 0
	v_mfma_f32_16x16x32_bf16 v[52:55], v[80:83], v[72:75], v[52:55]
	v_mfma_f32_16x16x32_bf16 v[52:55], v[84:87], v[64:67], v[52:55]
	v_mfma_f32_16x16x32_bf16 v[52:55], v[88:91], v[60:63], v[52:55]
	ds_read_b64_tr_b16 v[176:177], v201 offset:18432
	ds_read_b64_tr_b16 v[178:179], v201 offset:19008
	ds_read_b64_tr_b16 v[180:181], v201 offset:23040
	ds_read_b64_tr_b16 v[182:183], v201 offset:23616
	ds_read_b64_tr_b16 v[196:197], v201 offset:18464
	ds_read_b64_tr_b16 v[198:199], v201 offset:19040
	ds_read_b64_tr_b16 v[228:229], v201 offset:23072
	ds_read_b64_tr_b16 v[230:231], v201 offset:23648
	s_waitcnt lgkmcnt(8)
	v_mfma_f32_16x16x32_bf16 v[56:59], v[92:95], v[68:71], 0
	v_mfma_f32_16x16x32_bf16 v[56:59], v[96:99], v[72:75], v[56:59]
	v_mfma_f32_16x16x32_bf16 v[56:59], v[100:103], v[64:67], v[56:59]
	v_mfma_f32_16x16x32_bf16 v[56:59], v[172:175], v[60:63], v[56:59]
	ds_read_b64_tr_b16 v[76:77], v201 offset:18496
	ds_read_b64_tr_b16 v[78:79], v201 offset:19072
	ds_read_b64_tr_b16 v[80:81], v201 offset:23104
	ds_read_b64_tr_b16 v[82:83], v201 offset:23680
	s_waitcnt lgkmcnt(4)
	v_mfma_f32_16x16x32_bf16 v[36:39], v[176:179], v[64:67], v[36:39]
	v_mfma_f32_16x16x32_bf16 v[36:39], v[180:183], v[60:63], v[36:39]
	v_mfma_f32_16x16x32_bf16 v[32:35], v[196:199], v[64:67], v[32:35]
	v_mfma_f32_16x16x32_bf16 v[32:35], v[228:231], v[60:63], v[32:35]
	ds_read_b64_tr_b16 v[84:85], v201 offset:18528
	ds_read_b64_tr_b16 v[86:87], v201 offset:19104
	ds_read_b64_tr_b16 v[88:89], v201 offset:23136
	ds_read_b64_tr_b16 v[90:91], v201 offset:23712
	s_waitcnt lgkmcnt(4)
	v_mfma_f32_16x16x32_bf16 v[20:23], v[76:79], v[64:67], v[20:23]
	v_mfma_f32_16x16x32_bf16 v[20:23], v[80:83], v[60:63], v[20:23]
	s_waitcnt lgkmcnt(0)
	v_mfma_f32_16x16x32_bf16 v[16:19], v[84:87], v[64:67], v[16:19]
	v_mfma_f32_16x16x32_bf16 v[16:19], v[88:91], v[60:63], v[16:19]
